# v3 plus DSA attention units moved ahead of the second half of diff-attention units (longest-first tail packing)
# speedup vs baseline: 1.0789x; 1.0021x over previous
.Lq0_done:
	s_cmpk_lt_u32 s58, 1856
	s_cbranch_scc1 .Lq0_d2
	s_cmpk_ge_u32 s58, 2624
	s_cbranch_scc1 .Lq0_d2
	s_cmpk_ge_u32 s58, 2112
	s_cbranch_scc1 .Lq0_a2
	s_addk_i32 s58, 512
	s_branch .Lq0_d2
.Lq0_a2:
	s_addk_i32 s58, -256
